# skinny (sample-row) GEMM K-loops unrolled with 6 k-steps in flight and counted vmcnt waits
# speedup vs baseline: 1.0467x; 1.0019x over previous
; template <int KSPLIT, class F>
; __device__ __forceinline__ void skinny_gemm(const bf16_t* A, const bf16_t* Bt, int N, int K, const F& f, LAS unsigned char* lds, int bx, int G, int wave) {
;     ...
;     for (int t = bx; t < ntiles; t += G) {
;         const int rg = t % RG, n0 = (t / RG) * 16;
;         const int mt = rg * MTW + (wave % MTW), kq = wave / MTW;
;         const bf16_t* ap = A + (size_t)(MP + 16 * mt + fr) * K + kq * klen + 8 * fq;
;         const bf16_t* bp = Bt + (size_t)(n0 + fr) * K + kq * klen + 8 * fq;
;         f32x4 acc = (f32x4){0.f, 0.f, 0.f, 0.f};
; #pragma unroll 16
;         for (int k = 0; k < klen; k += 32) {
;             const bf16x8 af = *(const bf16x8*)(ap + k), bf = *(const bf16x8*)(bp + k);
;             acc = __builtin_amdgcn_mfma_f32_16x16x32_bf16(bf, af, acc, 0, 0, 0);
;         }
.LBB0_1486:
	v_lshl_add_u64 v[32:33], v[28:29], 0, v[22:23]
	v_lshl_add_u64 v[34:35], v[30:31], 0, v[22:23]
	global_load_dwordx4 v[180:183], v[32:33], off offset:-512
	global_load_dwordx4 v[184:187], v[34:35], off
	global_load_dwordx4 v[188:191], v[34:35], off offset:64
	global_load_dwordx4 v[192:195], v[32:33], off offset:-448
	global_load_dwordx4 v[196:199], v[34:35], off offset:128
	global_load_dwordx4 v[200:203], v[32:33], off offset:-384
	global_load_dwordx4 v[204:207], v[34:35], off offset:192
	global_load_dwordx4 v[214:217], v[32:33], off offset:-320
	global_load_dwordx4 v[234:237], v[34:35], off offset:256
	global_load_dwordx4 v[238:241], v[32:33], off offset:-256
	global_load_dwordx4 v[242:245], v[34:35], off offset:320
	global_load_dwordx4 v[246:249], v[32:33], off offset:-192
	s_waitcnt vmcnt(10)
	v_mfma_f32_16x16x32_bf16 v[4:7], v[180:183], v[184:187], v[4:7]
	global_load_dwordx4 v[180:183], v[34:35], off offset:384
	global_load_dwordx4 v[184:187], v[32:33], off offset:-128
	s_waitcnt vmcnt(10)
	v_mfma_f32_16x16x32_bf16 v[4:7], v[192:195], v[188:191], v[4:7]
	global_load_dwordx4 v[188:191], v[34:35], off offset:448
	global_load_dwordx4 v[192:195], v[32:33], off offset:-64
	s_waitcnt vmcnt(10)
	v_mfma_f32_16x16x32_bf16 v[4:7], v[200:203], v[196:199], v[4:7]
	global_load_dwordx4 v[196:199], v[34:35], off offset:512
	global_load_dwordx4 v[200:203], v[32:33], off
	s_waitcnt vmcnt(10)
	v_mfma_f32_16x16x32_bf16 v[4:7], v[214:217], v[204:207], v[4:7]
	global_load_dwordx4 v[204:207], v[34:35], off offset:576
	global_load_dwordx4 v[214:217], v[32:33], off offset:64
	s_waitcnt vmcnt(10)
	v_mfma_f32_16x16x32_bf16 v[4:7], v[238:241], v[234:237], v[4:7]
	global_load_dwordx4 v[234:237], v[34:35], off offset:640
	global_load_dwordx4 v[238:241], v[32:33], off offset:128
	s_waitcnt vmcnt(10)
	v_mfma_f32_16x16x32_bf16 v[4:7], v[246:249], v[242:245], v[4:7]
	global_load_dwordx4 v[242:245], v[34:35], off offset:704
	global_load_dwordx4 v[246:249], v[32:33], off offset:192
	s_waitcnt vmcnt(10)
	v_mfma_f32_16x16x32_bf16 v[4:7], v[184:187], v[180:183], v[4:7]
	global_load_dwordx4 v[180:183], v[34:35], off offset:768
	global_load_dwordx4 v[184:187], v[32:33], off offset:256
	s_waitcnt vmcnt(10)
	v_mfma_f32_16x16x32_bf16 v[4:7], v[192:195], v[188:191], v[4:7]
	global_load_dwordx4 v[188:191], v[34:35], off offset:832
	global_load_dwordx4 v[192:195], v[32:33], off offset:320
	s_waitcnt vmcnt(10)
	v_mfma_f32_16x16x32_bf16 v[4:7], v[200:203], v[196:199], v[4:7]
	global_load_dwordx4 v[196:199], v[34:35], off offset:896
	global_load_dwordx4 v[200:203], v[32:33], off offset:384
	s_waitcnt vmcnt(10)
	v_mfma_f32_16x16x32_bf16 v[4:7], v[214:217], v[204:207], v[4:7]
	global_load_dwordx4 v[204:207], v[34:35], off offset:960
	global_load_dwordx4 v[214:217], v[32:33], off offset:448
	s_waitcnt vmcnt(10)
	v_mfma_f32_16x16x32_bf16 v[4:7], v[238:241], v[234:237], v[4:7]
	global_load_dwordx4 v[234:237], v[32:33], off offset:512
	global_load_dwordx4 v[238:241], v[34:35], off offset:1024
	s_waitcnt vmcnt(10)
	v_mfma_f32_16x16x32_bf16 v[4:7], v[246:249], v[242:245], v[4:7]
	global_load_dwordx4 v[242:245], v[34:35], off offset:1088
	global_load_dwordx4 v[246:249], v[32:33], off offset:576
	s_waitcnt vmcnt(10)
	v_mfma_f32_16x16x32_bf16 v[4:7], v[184:187], v[180:183], v[4:7]
	global_load_dwordx4 v[180:183], v[34:35], off offset:1152
	global_load_dwordx4 v[184:187], v[32:33], off offset:640
	s_waitcnt vmcnt(10)
	v_mfma_f32_16x16x32_bf16 v[4:7], v[192:195], v[188:191], v[4:7]
	global_load_dwordx4 v[188:191], v[34:35], off offset:1216
	global_load_dwordx4 v[192:195], v[32:33], off offset:704
	s_waitcnt vmcnt(10)
	v_mfma_f32_16x16x32_bf16 v[4:7], v[200:203], v[196:199], v[4:7]
	global_load_dwordx4 v[196:199], v[34:35], off offset:1280
	global_load_dwordx4 v[200:203], v[32:33], off offset:768
	s_waitcnt vmcnt(10)
	v_mfma_f32_16x16x32_bf16 v[4:7], v[214:217], v[204:207], v[4:7]
	global_load_dwordx4 v[204:207], v[34:35], off offset:1344
	global_load_dwordx4 v[214:217], v[32:33], off offset:832
	s_waitcnt vmcnt(10)
	v_mfma_f32_16x16x32_bf16 v[4:7], v[234:237], v[238:241], v[4:7]
	global_load_dwordx4 v[234:237], v[34:35], off offset:1408
	global_load_dwordx4 v[238:241], v[32:33], off offset:896
	s_waitcnt vmcnt(10)
	v_mfma_f32_16x16x32_bf16 v[4:7], v[246:249], v[242:245], v[4:7]
	global_load_dwordx4 v[242:245], v[34:35], off offset:1472
	global_load_dwordx4 v[246:249], v[32:33], off offset:960
	s_waitcnt vmcnt(10)
	v_mfma_f32_16x16x32_bf16 v[4:7], v[184:187], v[180:183], v[4:7]
	global_load_dwordx4 v[180:183], v[34:35], off offset:1536
	global_load_dwordx4 v[184:187], v[32:33], off offset:1024
	s_waitcnt vmcnt(10)
	v_mfma_f32_16x16x32_bf16 v[4:7], v[192:195], v[188:191], v[4:7]
	global_load_dwordx4 v[188:191], v[34:35], off offset:1600
	global_load_dwordx4 v[192:195], v[32:33], off offset:1088
	s_waitcnt vmcnt(10)
	v_mfma_f32_16x16x32_bf16 v[4:7], v[200:203], v[196:199], v[4:7]
	global_load_dwordx4 v[196:199], v[34:35], off offset:1664
	global_load_dwordx4 v[200:203], v[32:33], off offset:1152
	s_waitcnt vmcnt(10)
	v_mfma_f32_16x16x32_bf16 v[4:7], v[214:217], v[204:207], v[4:7]
	global_load_dwordx4 v[204:207], v[34:35], off offset:1728
	global_load_dwordx4 v[214:217], v[32:33], off offset:1216
	s_waitcnt vmcnt(10)
	v_mfma_f32_16x16x32_bf16 v[4:7], v[238:241], v[234:237], v[4:7]
	global_load_dwordx4 v[234:237], v[34:35], off offset:1792
	global_load_dwordx4 v[238:241], v[32:33], off offset:1280
	s_waitcnt vmcnt(10)
	v_mfma_f32_16x16x32_bf16 v[4:7], v[246:249], v[242:245], v[4:7]
	global_load_dwordx4 v[242:245], v[34:35], off offset:1856
	global_load_dwordx4 v[246:249], v[32:33], off offset:1344
	s_waitcnt vmcnt(10)
	v_mfma_f32_16x16x32_bf16 v[4:7], v[184:187], v[180:183], v[4:7]
	global_load_dwordx4 v[180:183], v[34:35], off offset:1920
	global_load_dwordx4 v[184:187], v[32:33], off offset:1408
	s_waitcnt vmcnt(10)
	v_mfma_f32_16x16x32_bf16 v[4:7], v[192:195], v[188:191], v[4:7]
	global_load_dwordx4 v[188:191], v[34:35], off offset:1984
	global_load_dwordx4 v[192:195], v[32:33], off offset:1472
	s_waitcnt vmcnt(10)
	v_mfma_f32_16x16x32_bf16 v[4:7], v[200:203], v[196:199], v[4:7]
	s_waitcnt vmcnt(8)
	v_mfma_f32_16x16x32_bf16 v[4:7], v[214:217], v[204:207], v[4:7]
	s_waitcnt vmcnt(6)
	v_mfma_f32_16x16x32_bf16 v[4:7], v[238:241], v[234:237], v[4:7]
	s_waitcnt vmcnt(4)
	v_mfma_f32_16x16x32_bf16 v[4:7], v[246:249], v[242:245], v[4:7]
	s_waitcnt vmcnt(2)
	v_mfma_f32_16x16x32_bf16 v[4:7], v[184:187], v[180:183], v[4:7]
	s_waitcnt vmcnt(0)
	v_mfma_f32_16x16x32_bf16 v[4:7], v[192:195], v[188:191], v[4:7]
	s_nop 0
	v_lshl_add_u32 v28, s2, 4, v3
	s_andn2_b64 vcc, exec, s[96:97]
	s_cbranch_vccnz .LBB0_1489
; __device__ __forceinline__ void stats_sk(const float* sts, int row, int fq, float& mu, float& rs) {
;     const f32x4* p = (const f32x4*)(sts + (size_t)(row - MP) * 128 + fq * 32);
;     float s1 = 0.f, s2 = 0.f;
; #pragma unroll
;     for (int i = 0; i < 8; ++i) { const f32x4 a = p[i]; s1 += a.x + a.z; s2 += a.y + a.w; }
;     s1 += __shfl_xor(s1, 16); s2 += __shfl_xor(s2, 16); s1 += __shfl_xor(s1, 32); s2 += __shfl_xor(s2, 32);
;     mu = s1 * (1.f / DM); rs = __builtin_amdgcn_rsqf(fmaxf(s2 * (1.f / DM) - mu * mu, 0.f) + LN_EPS);
; }
;     __device__ __forceinline__ void sk(int row, int col, f32x4 v, int fq) const {
;         if (fold) { float mu, rs; stats_sk(sts, row, fq, mu, rs); const f32x4 c1v = *(const f32x4*)(c1 + col), c2v = *(const f32x4*)(c2 + col); v = (v - c1v * mu) * rs + c2v; }
;         float d1 = 0.f, d2 = 0.f; f(row, col, v, fq, d1, d2);
;     }
	global_load_dwordx4 v[30:33], v[0:1], off offset:48
	global_load_dwordx4 v[34:37], v[0:1], off offset:32
	global_load_dwordx4 v[38:41], v[0:1], off offset:16
	global_load_dwordx4 v[42:45], v[0:1], off
	global_load_dwordx4 v[46:49], v[0:1], off offset:112
	global_load_dwordx4 v[50:53], v[0:1], off offset:96
	global_load_dwordx4 v[54:57], v[0:1], off offset:80
	global_load_dwordx4 v[58:61], v[0:1], off offset:64
	v_and_b32_e32 v29, 64, v219
	v_xor_b32_e32 v25, 16, v219
	v_add_u32_e32 v29, 64, v29
	v_cmp_lt_i32_e32 vcc, v25, v29
	v_xor_b32_e32 v62, 32, v219
	v_readlane_b32 s0, v250, 35
	v_cndmask_b32_e32 v25, v219, v25, vcc
	v_lshlrev_b32_e32 v25, 2, v25
	v_cmp_lt_i32_e32 vcc, v62, v29
	v_readlane_b32 s1, v250, 36
	s_waitcnt vmcnt(7)
	v_pk_add_f32 v[30:31], v[30:31], v[32:33]
	s_waitcnt vmcnt(6)
	v_pk_add_f32 v[34:35], v[34:35], v[36:37]
	s_waitcnt vmcnt(5)
	v_pk_add_f32 v[38:39], v[38:39], v[40:41]
	s_waitcnt vmcnt(4)
	v_pk_add_f32 v[42:43], v[42:43], v[44:45]
	v_cndmask_b32_e32 v29, v219, v62, vcc
	v_pk_add_f32 v[42:43], v[42:43], 0 op_sel_hi:[1,0]
	v_lshlrev_b32_e32 v29, 2, v29
	v_pk_add_f32 v[38:39], v[42:43], v[38:39]
	s_waitcnt vmcnt(0)
	v_pk_add_f32 v[32:33], v[58:59], v[60:61]
	v_pk_add_f32 v[34:35], v[38:39], v[34:35]
	s_nop 0
	v_pk_add_f32 v[30:31], v[34:35], v[30:31]
	s_nop 0
	v_pk_add_f32 v[30:31], v[30:31], v[32:33]
	v_pk_add_f32 v[32:33], v[54:55], v[56:57]
	s_nop 0
	v_pk_add_f32 v[30:31], v[30:31], v[32:33]
	v_pk_add_f32 v[32:33], v[50:51], v[52:53]
	s_nop 0
	v_pk_add_f32 v[30:31], v[30:31], v[32:33]
	v_pk_add_f32 v[32:33], v[46:47], v[48:49]
	s_nop 0
	v_pk_add_f32 v[30:31], v[30:31], v[32:33]
	ds_bpermute_b32 v32, v25, v30
	ds_bpermute_b32 v33, v25, v31
	s_waitcnt lgkmcnt(0)
	v_pk_add_f32 v[30:31], v[30:31], v[32:33]
	ds_bpermute_b32 v32, v29, v30
	ds_bpermute_b32 v33, v29, v31
	v_ashrrev_i32_e32 v29, 31, v28
	v_lshlrev_b64 v[38:39], 2, v[28:29]
	v_lshl_add_u64 v[34:35], s[0:1], 0, v[38:39]
	global_load_dwordx4 v[34:37], v[34:35], off
	v_lshl_add_u64 v[38:39], s[64:65], 0, v[38:39]
	global_load_dwordx4 v[38:41], v[38:39], off
	s_waitcnt lgkmcnt(0)
	v_pk_add_f32 v[30:31], v[30:31], v[32:33]
	s_nop 0
	v_pk_mul_f32 v[32:33], v[30:31], s[82:83] op_sel_hi:[1,0]
	s_nop 0
	v_fma_f32 v25, -v32, v32, v33
	v_max_f32_e32 v25, 0, v25
	v_add_f32_e32 v25, 0x3727c5ac, v25
	v_rsq_f32_e32 v30, v25
	s_waitcnt vmcnt(1)
	v_pk_fma_f32 v[4:5], v[34:35], v[32:33], v[4:5] op_sel_hi:[1,0,1] neg_lo:[1,0,0] neg_hi:[1,0,0]
	v_xor_b32_e32 v35, 0x80000000, v37
	v_xor_b32_e32 v34, 0x80000000, v36
	v_pk_fma_f32 v[6:7], v[34:35], v[32:33], v[6:7] op_sel_hi:[1,0,1]
	s_waitcnt vmcnt(0)
	v_pk_fma_f32 v[4:5], v[4:5], v[30:31], v[38:39] op_sel_hi:[1,0,1]
	v_pk_fma_f32 v[6:7], v[6:7], v[30:31], v[40:41] op_sel_hi:[1,0,1]

; #define LAS __attribute__((address_space(3)))
;     __device__ __forceinline__ void sk(int row, int col, f32x4 v, int fq) const {
;         float mu = 0.f, rs = 1.f; if (ln) stats_sk(sts_p, row, fq, mu, rs);
; template <int KSPLIT, class F>
; __device__ __forceinline__ void skinny_gemm(const bf16_t* A, const bf16_t* Bt, int N, int K, const F& f, LAS unsigned char* lds, int bx, int G, int wave) {
;     ...
;         const bf16_t* ap = A + (size_t)(MP + 16 * mt + fr) * K + kq * klen + 8 * fq;
;         const bf16_t* bp = Bt + (size_t)(n0 + fr) * K + kq * klen + 8 * fq;
;         f32x4 acc = (f32x4){0.f, 0.f, 0.f, 0.f};
; #pragma unroll 16
;         for (int k = 0; k < klen; k += 32) {
;             const bf16x8 af = *(const bf16x8*)(ap + k), bf = *(const bf16x8*)(bp + k);
;             acc = __builtin_amdgcn_mfma_f32_16x16x32_bf16(bf, af, acc, 0, 0, 0);
;         }
;         if (KSPLIT > 1) {
;             __syncthreads();
;             *(LAS f32x4*)(lds + wave * 1024 + lane * 16) = acc;
;             __syncthreads();
;             if (kq == 0) {
; #pragma unroll
;                 for (int q = 1; q < KSPLIT; ++q) acc = acc + *(const LAS f32x4*)(lds + (wave + q * MTW) * 1024 + lane * 16);
;                 f.sk(MP + 16 * mt + fr, n0 + 4 * fq, acc, fq);
;             }
;         } else f.sk(MP + 16 * mt + fr, n0 + 4 * fq, acc, fq);
.LBB0_1948:
	s_ashr_i32 s0, s4, 31
	s_lshr_b32 s0, s0, 30
	s_add_i32 s0, s4, s0
	s_ashr_i32 s8, s0, 2
	s_lshl_b32 s1, s8, 7
	v_subrev_u32_e32 v24, s1, v39
	v_add_u32_e32 v4, 0x4000, v24
	v_mov_b32_e32 v5, v2
	s_lshl_b32 s0, s8, 4
	v_lshlrev_b64 v[4:5], 11, v[4:5]
	v_lshl_add_u64 v[16:17], v[0:1], 0, v[4:5]
	v_or_b32_e32 v4, s0, v3
	v_ashrrev_i32_e32 v5, 31, v4
	v_lshlrev_b64 v[4:5], 11, v[4:5]
	v_lshl_add_u64 v[18:19], v[20:21], 0, v[4:5]
	s_waitcnt lgkmcnt(0)
	v_readlane_b32 s10, v253, 39
	v_readlane_b32 s11, v253, 40
	s_andn2_b64 vcc, exec, s[10:11]
	global_load_dwordx4 v[180:183], v[16:17], off
	global_load_dwordx4 v[184:187], v[18:19], off
	global_load_dwordx4 v[188:191], v[16:17], off offset:64
	global_load_dwordx4 v[192:195], v[18:19], off offset:64
	global_load_dwordx4 v[196:199], v[16:17], off offset:128
	global_load_dwordx4 v[200:203], v[18:19], off offset:128
	global_load_dwordx4 v[204:207], v[16:17], off offset:192
	global_load_dwordx4 v[214:217], v[18:19], off offset:192
	global_load_dwordx4 v[234:237], v[16:17], off offset:256
	global_load_dwordx4 v[238:241], v[18:19], off offset:256
	global_load_dwordx4 v[242:245], v[16:17], off offset:320
	global_load_dwordx4 v[246:249], v[18:19], off offset:320
	s_waitcnt vmcnt(10)
	v_mfma_f32_16x16x32_bf16 v[4:7], v[184:187], v[180:183], 0
	global_load_dwordx4 v[180:183], v[16:17], off offset:384
	global_load_dwordx4 v[184:187], v[18:19], off offset:384
	s_waitcnt vmcnt(10)
	v_mfma_f32_16x16x32_bf16 v[4:7], v[192:195], v[188:191], v[4:7]
	global_load_dwordx4 v[188:191], v[16:17], off offset:448
	global_load_dwordx4 v[192:195], v[18:19], off offset:448
	s_waitcnt vmcnt(10)
	v_mfma_f32_16x16x32_bf16 v[4:7], v[200:203], v[196:199], v[4:7]
	s_waitcnt vmcnt(8)
	v_mfma_f32_16x16x32_bf16 v[4:7], v[214:217], v[204:207], v[4:7]
	s_waitcnt vmcnt(6)
	v_mfma_f32_16x16x32_bf16 v[4:7], v[238:241], v[234:237], v[4:7]
	s_waitcnt vmcnt(4)
	v_mfma_f32_16x16x32_bf16 v[4:7], v[246:249], v[242:245], v[4:7]
	s_waitcnt vmcnt(2)
	v_mfma_f32_16x16x32_bf16 v[4:7], v[184:187], v[180:183], v[4:7]
	s_barrier
	s_waitcnt vmcnt(0)
	v_mfma_f32_16x16x32_bf16 v[4:7], v[192:195], v[188:191], v[4:7]
	s_nop 7
	ds_write_b128 v41, v[4:7]
	s_waitcnt lgkmcnt(0)
	s_barrier
	s_cbranch_vccnz .LBB0_1947
	ds_read_b128 v[16:19], v41 offset:2048
	ds_read_b128 v[12:15], v41 offset:4096
	ds_read_b128 v[8:11], v41 offset:6144
	v_cndmask_b32_e64 v25, 0, 1, s[96:97]
	v_cmp_ne_u32_e64 s[40:41], 1, v25
	s_andn2_b64 vcc, exec, s[96:97]
	v_ashrrev_i32_e32 v25, 31, v24
	s_cbranch_vccnz .LBB0_1951
	v_lshlrev_b64 v[26:27], 9, v[24:25]
	v_lshl_add_u64 v[54:55], v[22:23], 0, v[26:27]
	global_load_dwordx4 v[42:45], v[54:55], off offset:48
	global_load_dwordx4 v[26:29], v[54:55], off offset:32
	global_load_dwordx4 v[46:49], v[54:55], off offset:16
	global_load_dwordx4 v[30:33], v[54:55], off
	s_waitcnt vmcnt(1)
	v_add_f32_e32 v34, v47, v49
	s_waitcnt vmcnt(0)
	v_add_f32_e32 v36, v31, v33
	v_mov_b32_e32 v31, v46
	v_mov_b32_e32 v33, v48
	v_pk_add_f32 v[32:33], v[30:31], v[32:33]
	v_add_f32_e32 v30, v27, v29
	v_mov_b32_e32 v27, v42
	v_mov_b32_e32 v29, v44
	v_pk_add_f32 v[26:27], v[26:27], v[28:29]
	v_add_f32_e32 v28, v43, v45
	global_load_dwordx4 v[42:45], v[54:55], off offset:112
	global_load_dwordx4 v[46:49], v[54:55], off offset:96
	global_load_dwordx4 v[50:53], v[54:55], off offset:80
	s_nop 0
	global_load_dwordx4 v[54:57], v[54:55], off offset:64
	v_and_b32_e32 v31, 64, v219
	v_xor_b32_e32 v29, 16, v219
	v_add_u32_e32 v31, 64, v31
	v_cmp_lt_i32_e32 vcc, v29, v31
	v_mov_b32_e32 v37, v32
	v_pk_add_f32 v[36:37], v[36:37], 0 op_sel_hi:[1,0]
	v_cndmask_b32_e32 v29, v219, v29, vcc
	v_mov_b32_e32 v35, v33
	v_pk_add_f32 v[32:33], v[36:37], v[34:35]
	s_waitcnt vmcnt(0)
	v_add_f32_e32 v58, v55, v57
	v_mov_b32_e32 v57, v52
	v_add_f32_e32 v52, v47, v49
	v_mov_b32_e32 v49, v44
	v_lshlrev_b32_e32 v44, 2, v29
	v_xor_b32_e32 v29, 32, v219
	v_cmp_lt_i32_e32 vcc, v29, v31
	v_mov_b32_e32 v55, v50
	v_mov_b32_e32 v31, v26
	v_cndmask_b32_e32 v29, v219, v29, vcc
	v_pk_add_f32 v[54:55], v[54:55], v[56:57]
	v_mov_b32_e32 v47, v42
	v_add_f32_e32 v42, v43, v45
	v_lshlrev_b32_e32 v45, 2, v29
	v_pk_add_f32 v[30:31], v[32:33], v[30:31]
	v_mov_b32_e32 v29, v27
	v_pk_add_f32 v[26:27], v[30:31], v[28:29]
	v_mov_b32_e32 v59, v54
	v_add_f32_e32 v50, v51, v53
	v_pk_add_f32 v[46:47], v[46:47], v[48:49]
	v_pk_add_f32 v[26:27], v[26:27], v[58:59]
	v_mov_b32_e32 v51, v55
	v_pk_add_f32 v[26:27], v[26:27], v[50:51]
	v_mov_b32_e32 v53, v46
	v_pk_add_f32 v[26:27], v[26:27], v[52:53]
	v_mov_b32_e32 v43, v47
	v_pk_add_f32 v[26:27], v[26:27], v[42:43]
	ds_bpermute_b32 v29, v44, v27
	ds_bpermute_b32 v28, v44, v26
	s_waitcnt lgkmcnt(0)
	v_pk_add_f32 v[26:27], v[26:27], v[28:29]
	ds_bpermute_b32 v29, v45, v27
	ds_bpermute_b32 v28, v45, v26
	s_waitcnt lgkmcnt(0)
	v_pk_add_f32 v[26:27], v[26:27], v[28:29]
	s_nop 0
	v_pk_mul_f32 v[30:31], v[26:27], s[82:83] op_sel_hi:[1,0]
	s_nop 0
	v_fma_f32 v26, -v31, v31, v30
	v_max_f32_e32 v26, 0, v26
	v_add_f32_e32 v26, 0x3727c5ac, v26
	v_rsq_f32_e32 v30, v26
	s_branch .LBB0_1952

; #define LAS __attribute__((address_space(3)))
;     __device__ __forceinline__ void sk(int row, int col, f32x4 v, int fq) const {
;         if (fold) { float mu, rs; stats_sk(sts, row, fq, mu, rs); const f32x4 c1v = *(const f32x4*)(c1 + col), c2v = *(const f32x4*)(c2 + col); v = (v - c1v * mu) * rs + c2v; }
;         float d1 = 0.f, d2 = 0.f; f(row, col, v, fq, d1, d2);
; template <int KSPLIT, class F>
; __device__ __forceinline__ void skinny_gemm(const bf16_t* A, const bf16_t* Bt, int N, int K, const F& f, LAS unsigned char* lds, int bx, int G, int wave) {
;     ...
;         const bf16_t* ap = A + (size_t)(MP + 16 * mt + fr) * K + kq * klen + 8 * fq;
;         const bf16_t* bp = Bt + (size_t)(n0 + fr) * K + kq * klen + 8 * fq;
;         f32x4 acc = (f32x4){0.f, 0.f, 0.f, 0.f};
; #pragma unroll 16
;         for (int k = 0; k < klen; k += 32) {
;             const bf16x8 af = *(const bf16x8*)(ap + k), bf = *(const bf16x8*)(bp + k);
;             acc = __builtin_amdgcn_mfma_f32_16x16x32_bf16(bf, af, acc, 0, 0, 0);
;         }
;         if (KSPLIT > 1) {
;             __syncthreads();
;             *(LAS f32x4*)(lds + wave * 1024 + lane * 16) = acc;
;             __syncthreads();
;             if (kq == 0) {
; #pragma unroll
;                 for (int q = 1; q < KSPLIT; ++q) acc = acc + *(const LAS f32x4*)(lds + (wave + q * MTW) * 1024 + lane * 16);
;                 f.sk(MP + 16 * mt + fr, n0 + 4 * fq, acc, fq);
;             }
;         } else f.sk(MP + 16 * mt + fr, n0 + 4 * fq, acc, fq);
.LBB0_2033:
	s_ashr_i32 s1, s0, 31
	s_lshr_b32 s1, s1, 30
	s_add_i32 s1, s0, s1
	s_ashr_i32 s2, s1, 2
	s_lshl_b32 s1, s2, 4
	s_lshl_b32 s2, s2, 7
	v_subrev_u32_e32 v16, s2, v19
	v_add_u32_e32 v4, 0x4000, v16
	v_mov_b32_e32 v5, v2
	v_lshlrev_b64 v[12:13], 11, v[4:5]
	v_or_b32_e32 v4, s1, v3
	v_ashrrev_i32_e32 v5, 31, v4
	v_lshl_add_u64 v[14:15], v[0:1], 0, v[12:13]
	v_lshlrev_b64 v[4:5], 11, v[4:5]
	v_lshl_add_u64 v[30:31], v[8:9], 0, v[4:5]
	v_readlane_b32 s8, v253, 39
	v_readlane_b32 s9, v253, 40
	s_andn2_b64 vcc, exec, s[8:9]
	global_load_dwordx4 v[180:183], v[14:15], off
	global_load_dwordx4 v[184:187], v[30:31], off
	global_load_dwordx4 v[188:191], v[14:15], off offset:64
	global_load_dwordx4 v[192:195], v[30:31], off offset:64
	global_load_dwordx4 v[196:199], v[14:15], off offset:128
	global_load_dwordx4 v[200:203], v[30:31], off offset:128
	global_load_dwordx4 v[204:207], v[14:15], off offset:192
	global_load_dwordx4 v[214:217], v[30:31], off offset:192
	global_load_dwordx4 v[234:237], v[14:15], off offset:256
	global_load_dwordx4 v[238:241], v[30:31], off offset:256
	global_load_dwordx4 v[242:245], v[14:15], off offset:320
	global_load_dwordx4 v[246:249], v[30:31], off offset:320
	s_waitcnt vmcnt(10)
	v_mfma_f32_16x16x32_bf16 v[4:7], v[184:187], v[180:183], 0
	global_load_dwordx4 v[180:183], v[14:15], off offset:384
	global_load_dwordx4 v[184:187], v[30:31], off offset:384
	s_waitcnt vmcnt(10)
	v_mfma_f32_16x16x32_bf16 v[4:7], v[192:195], v[188:191], v[4:7]
	global_load_dwordx4 v[188:191], v[14:15], off offset:448
	global_load_dwordx4 v[192:195], v[30:31], off offset:448
	s_waitcnt vmcnt(10)
	v_mfma_f32_16x16x32_bf16 v[4:7], v[200:203], v[196:199], v[4:7]
	s_waitcnt vmcnt(8)
	v_mfma_f32_16x16x32_bf16 v[4:7], v[214:217], v[204:207], v[4:7]
	s_waitcnt vmcnt(6)
	v_mfma_f32_16x16x32_bf16 v[4:7], v[238:241], v[234:237], v[4:7]
	s_waitcnt vmcnt(4)
	v_mfma_f32_16x16x32_bf16 v[4:7], v[246:249], v[242:245], v[4:7]
	s_waitcnt vmcnt(2)
	v_mfma_f32_16x16x32_bf16 v[4:7], v[184:187], v[180:183], v[4:7]
	s_barrier
	s_waitcnt vmcnt(0)
	v_mfma_f32_16x16x32_bf16 v[4:7], v[192:195], v[188:191], v[4:7]
	s_nop 7
	ds_write_b128 v20, v[4:7]
	s_waitcnt lgkmcnt(0)
	s_barrier
	s_cbranch_vccnz .LBB0_2032
	ds_read_b128 v[22:25], v20 offset:2048
	v_ashrrev_i32_e32 v17, 31, v16
	v_lshlrev_b64 v[16:17], 9, v[16:17]
	v_lshl_add_u64 v[16:17], v[10:11], 0, v[16:17]
	v_readlane_b32 s8, v252, 19
	s_waitcnt lgkmcnt(0)
	v_pk_add_f32 v[14:15], v[6:7], v[24:25]
	v_pk_add_f32 v[22:23], v[4:5], v[22:23]
	ds_read_b128 v[4:7], v20 offset:4096
	v_readlane_b32 s9, v252, 20
	s_waitcnt lgkmcnt(0)
	v_pk_add_f32 v[14:15], v[14:15], v[6:7]
	v_pk_add_f32 v[22:23], v[22:23], v[4:5]
	ds_read_b128 v[4:7], v20 offset:6144
	v_lshl_add_u64 v[12:13], s[8:9], 0, v[12:13]
	s_waitcnt lgkmcnt(0)
	v_pk_add_f32 v[6:7], v[14:15], v[6:7]
	v_pk_add_f32 v[14:15], v[22:23], v[4:5]
	global_load_dwordx4 v[22:25], v[16:17], off offset:48
	global_load_dwordx4 v[26:29], v[16:17], off offset:32
	global_load_dwordx4 v[30:33], v[16:17], off offset:16
	global_load_dwordx4 v[34:37], v[16:17], off
	global_load_dwordx4 v[38:41], v[16:17], off offset:112
	global_load_dwordx4 v[42:45], v[16:17], off offset:96
	global_load_dwordx4 v[46:49], v[16:17], off offset:80
	global_load_dwordx4 v[50:53], v[16:17], off offset:64
	v_and_b32_e32 v16, 64, v219
	v_xor_b32_e32 v5, 16, v219
	v_add_u32_e32 v16, 64, v16
	v_cmp_lt_i32_e32 vcc, v5, v16
	v_xor_b32_e32 v17, 32, v219
	v_add_u32_e32 v4, s1, v18
	v_cndmask_b32_e32 v5, v219, v5, vcc
	v_cmp_lt_i32_e32 vcc, v17, v16
	v_lshlrev_b32_e32 v5, 2, v5
	s_waitcnt vmcnt(7)
	v_pk_add_f32 v[22:23], v[22:23], v[24:25]
	v_cndmask_b32_e32 v16, v219, v17, vcc
	v_lshlrev_b32_e32 v21, 2, v16
	s_waitcnt vmcnt(4)
	v_pk_add_f32 v[16:17], v[34:35], v[36:37]
	v_pk_add_f32 v[30:31], v[30:31], v[32:33]
	v_pk_add_f32 v[16:17], v[16:17], 0 op_sel_hi:[1,0]
	v_pk_add_f32 v[26:27], v[26:27], v[28:29]
	v_pk_add_f32 v[16:17], v[16:17], v[30:31]
	s_nop 0
	v_pk_add_f32 v[16:17], v[16:17], v[26:27]
	s_nop 0
	v_pk_add_f32 v[16:17], v[16:17], v[22:23]
	s_waitcnt vmcnt(0)
	v_pk_add_f32 v[22:23], v[50:51], v[52:53]
	s_nop 0
	v_pk_add_f32 v[16:17], v[16:17], v[22:23]
	v_pk_add_f32 v[22:23], v[46:47], v[48:49]
	s_nop 0
	v_pk_add_f32 v[16:17], v[16:17], v[22:23]
	v_pk_add_f32 v[22:23], v[42:43], v[44:45]
	s_nop 0
	v_pk_add_f32 v[16:17], v[16:17], v[22:23]
	v_pk_add_f32 v[22:23], v[38:39], v[40:41]
	s_nop 0
	v_pk_add_f32 v[16:17], v[16:17], v[22:23]
	ds_bpermute_b32 v22, v5, v16
	ds_bpermute_b32 v23, v5, v17
	s_waitcnt lgkmcnt(0)
	v_pk_add_f32 v[16:17], v[16:17], v[22:23]
	ds_bpermute_b32 v22, v21, v16
	ds_bpermute_b32 v23, v21, v17
	s_waitcnt lgkmcnt(0)
	v_pk_add_f32 v[16:17], v[16:17], v[22:23]
	s_nop 0
	v_pk_mul_f32 v[16:17], v[16:17], s[82:83] op_sel_hi:[1,0]
	s_nop 0
	v_fma_f32 v5, -v16, v16, v17
	v_max_f32_e32 v5, 0, v5
	v_add_f32_e32 v5, 0x3727c5ac, v5
	v_rsq_f32_e32 v30, v5
	v_ashrrev_i32_e32 v5, 31, v4
	v_lshlrev_b64 v[26:27], 2, v[4:5]
	v_lshl_add_u64 v[22:23], s[42:43], 0, v[26:27]
	global_load_dwordx4 v[22:25], v[22:23], off
	v_lshl_add_u64 v[26:27], s[46:47], 0, v[26:27]
	global_load_dwordx4 v[26:29], v[26:27], off
	v_lshl_add_u64 v[4:5], v[4:5], 1, v[12:13]
	s_waitcnt vmcnt(1)
	v_xor_b32_e32 v25, 0x80000000, v25
	v_xor_b32_e32 v24, 0x80000000, v24
	v_pk_fma_f32 v[6:7], v[24:25], v[16:17], v[6:7] op_sel_hi:[1,0,1]
	v_pk_fma_f32 v[14:15], v[22:23], v[16:17], v[14:15] op_sel_hi:[1,0,1] neg_lo:[1,0,0] neg_hi:[1,0,0]
	s_waitcnt vmcnt(0)
	v_pk_fma_f32 v[6:7], v[6:7], v[30:31], v[28:29] op_sel_hi:[1,0,1]
	v_pk_fma_f32 v[14:15], v[14:15], v[30:31], v[26:27] op_sel_hi:[1,0,1]
	v_pk_mul_f32 v[16:17], v[6:7], s[84:85] op_sel_hi:[1,0]
	v_pk_mul_f32 v[6:7], v[14:15], s[84:85] op_sel_hi:[1,0]
	s_nop 0
	v_cvt_pk_bf16_f32 v6, v6, v7
	v_cvt_pk_bf16_f32 v7, v16, v17
	global_store_dwordx2 v[4:5], v[6:7], off
	s_branch .LBB0_2032

; #define LAS __attribute__((address_space(3)))
; __device__ __forceinline__ u32x2 pk4(f32x4 v) { u32x2 r; r.x = pk2(v.x, v.y); r.y = pk2(v.z, v.w); return r; }
;     __device__ __forceinline__ void sk(int row, int col, f32x4 v, int fq) const {
;         float mu = 0.f, rs = 1.f; if (ln) stats_sk(sts_p, row, fq, mu, rs);
;         const u32x2 raw = *(const u32x2*)(src + (size_t)row * DM + col);
;         f32x4 x = (f32x4){bflo(raw.x), bfhi(raw.x), bflo(raw.y), bfhi(raw.y)};
;         if (ln) x = (x - mu) * rs * *(const f32x4*)(g + col) + *(const f32x4*)(b + col);
;         const u32x2 pz = pk4(x * ALPHA + v);
;         *(u32x2*)(dst + (size_t)row * DM + col) = pz;
;         const float z0 = bflo(pz.x), z1 = bfhi(pz.x), z2 = bflo(pz.y), z3 = bfhi(pz.y);
;         float s1 = (z0 + z1) + (z2 + z3), s2 = (z0 * z0 + z1 * z1) + (z2 * z2 + z3 * z3);
;         s1 += __shfl_xor(s1, 16); s2 += __shfl_xor(s2, 16); s1 += __shfl_xor(s1, 32); s2 += __shfl_xor(s2, 32);
;         if (fq == 0) { float* p = sts_n + (size_t)(row - MP) * 128 + (col >> 4) * 2; p[0] = s1; p[1] = s2; }
;     }
; template <int KSPLIT, class F>
; __device__ __forceinline__ void skinny_gemm(const bf16_t* A, const bf16_t* Bt, int N, int K, const F& f, LAS unsigned char* lds, int bx, int G, int wave) {
;     ...
;         const bf16_t* ap = A + (size_t)(MP + 16 * mt + fr) * K + kq * klen + 8 * fq;
;         const bf16_t* bp = Bt + (size_t)(n0 + fr) * K + kq * klen + 8 * fq;
;         f32x4 acc = (f32x4){0.f, 0.f, 0.f, 0.f};
; #pragma unroll 16
;         for (int k = 0; k < klen; k += 32) {
;             const bf16x8 af = *(const bf16x8*)(ap + k), bf = *(const bf16x8*)(bp + k);
;             acc = __builtin_amdgcn_mfma_f32_16x16x32_bf16(bf, af, acc, 0, 0, 0);
;         }
;         if (KSPLIT > 1) {
;             __syncthreads();
;             *(LAS f32x4*)(lds + wave * 1024 + lane * 16) = acc;
;             __syncthreads();
;             if (kq == 0) {
; #pragma unroll
;                 for (int q = 1; q < KSPLIT; ++q) acc = acc + *(const LAS f32x4*)(lds + (wave + q * MTW) * 1024 + lane * 16);
;                 f.sk(MP + 16 * mt + fr, n0 + 4 * fq, acc, fq);
;             }
;         } else f.sk(MP + 16 * mt + fr, n0 + 4 * fq, acc, fq);
.LBB0_2227:
	s_ashr_i32 s0, s4, 31
	s_lshr_b32 s0, s0, 30
	s_add_i32 s0, s4, s0
	s_ashr_i32 s8, s0, 2
	s_lshl_b32 s1, s8, 7
	v_subrev_u32_e32 v12, s1, v23
	v_add_u32_e32 v4, 0x4000, v12
	v_mov_b32_e32 v5, v2
	s_lshl_b32 s0, s8, 4
	v_lshlrev_b64 v[4:5], 11, v[4:5]
	v_lshl_add_u64 v[26:27], v[0:1], 0, v[4:5]
	v_or_b32_e32 v4, s0, v3
	v_ashrrev_i32_e32 v5, 31, v4
	v_lshlrev_b64 v[4:5], 11, v[4:5]
	v_lshl_add_u64 v[28:29], v[8:9], 0, v[4:5]
	s_waitcnt lgkmcnt(0)
	v_readlane_b32 s10, v253, 39
	v_readlane_b32 s11, v253, 40
	s_andn2_b64 vcc, exec, s[10:11]
	global_load_dwordx4 v[180:183], v[26:27], off
	global_load_dwordx4 v[184:187], v[28:29], off
	global_load_dwordx4 v[188:191], v[26:27], off offset:64
	global_load_dwordx4 v[192:195], v[28:29], off offset:64
	global_load_dwordx4 v[196:199], v[26:27], off offset:128
	global_load_dwordx4 v[200:203], v[28:29], off offset:128
	global_load_dwordx4 v[204:207], v[26:27], off offset:192
	global_load_dwordx4 v[214:217], v[28:29], off offset:192
	global_load_dwordx4 v[234:237], v[26:27], off offset:256
	global_load_dwordx4 v[238:241], v[28:29], off offset:256
	global_load_dwordx4 v[242:245], v[26:27], off offset:320
	global_load_dwordx4 v[246:249], v[28:29], off offset:320
	s_waitcnt vmcnt(10)
	v_mfma_f32_16x16x32_bf16 v[4:7], v[184:187], v[180:183], 0
	global_load_dwordx4 v[180:183], v[26:27], off offset:384
	global_load_dwordx4 v[184:187], v[28:29], off offset:384
	s_waitcnt vmcnt(10)
	v_mfma_f32_16x16x32_bf16 v[4:7], v[192:195], v[188:191], v[4:7]
	global_load_dwordx4 v[188:191], v[26:27], off offset:448
	global_load_dwordx4 v[192:195], v[28:29], off offset:448
	s_waitcnt vmcnt(10)
	v_mfma_f32_16x16x32_bf16 v[4:7], v[200:203], v[196:199], v[4:7]
	s_waitcnt vmcnt(8)
	v_mfma_f32_16x16x32_bf16 v[4:7], v[214:217], v[204:207], v[4:7]
	s_waitcnt vmcnt(6)
	v_mfma_f32_16x16x32_bf16 v[4:7], v[238:241], v[234:237], v[4:7]
	s_waitcnt vmcnt(4)
	v_mfma_f32_16x16x32_bf16 v[4:7], v[246:249], v[242:245], v[4:7]
	s_waitcnt vmcnt(2)
	v_mfma_f32_16x16x32_bf16 v[4:7], v[184:187], v[180:183], v[4:7]
	s_barrier
	s_waitcnt vmcnt(0)
	v_mfma_f32_16x16x32_bf16 v[4:7], v[192:195], v[188:191], v[4:7]
	s_nop 7
	ds_write_b128 v25, v[4:7]
	s_waitcnt lgkmcnt(0)
	s_barrier
	s_cbranch_vccnz .LBB0_2226
	ds_read_b128 v[14:17], v25 offset:2048
	v_ashrrev_i32_e32 v13, 31, v12
	v_lshlrev_b64 v[12:13], 9, v[12:13]
	v_lshl_add_u64 v[20:21], v[10:11], 0, v[12:13]
	s_waitcnt lgkmcnt(0)
	v_pk_add_f32 v[16:17], v[6:7], v[16:17]
	v_pk_add_f32 v[14:15], v[4:5], v[14:15]
	ds_read_b128 v[4:7], v25 offset:4096
	s_waitcnt lgkmcnt(0)
	v_pk_add_f32 v[6:7], v[16:17], v[6:7]
	v_pk_add_f32 v[18:19], v[14:15], v[4:5]
	ds_read_b128 v[14:17], v25 offset:6144
	s_waitcnt lgkmcnt(0)
	v_pk_add_f32 v[4:5], v[6:7], v[16:17]
	v_pk_add_f32 v[6:7], v[18:19], v[14:15]
	global_load_dwordx4 v[16:19], v[20:21], off offset:48
	global_load_dwordx4 v[28:31], v[20:21], off offset:32
	global_load_dwordx4 v[32:35], v[20:21], off offset:16
	global_load_dwordx4 v[36:39], v[20:21], off
	global_load_dwordx4 v[40:43], v[20:21], off offset:112
	global_load_dwordx4 v[44:47], v[20:21], off offset:96
	global_load_dwordx4 v[48:51], v[20:21], off offset:80
	global_load_dwordx4 v[52:55], v[20:21], off offset:64
	v_and_b32_e32 v20, 64, v219
	v_xor_b32_e32 v15, 16, v219
	v_add_u32_e32 v20, 64, v20
	v_cmp_lt_i32_e32 vcc, v15, v20
	v_add_u32_e32 v14, s0, v22
	s_lshl_b32 s0, s8, 17
	v_cndmask_b32_e32 v15, v219, v15, vcc
	v_lshlrev_b32_e32 v27, 2, v15
	v_xor_b32_e32 v15, 32, v219
	v_cmp_lt_i32_e32 vcc, v15, v20
	s_waitcnt vmcnt(7)
	v_pk_add_f32 v[16:17], v[16:17], v[18:19]
	s_waitcnt vmcnt(6)
	v_pk_add_f32 v[28:29], v[28:29], v[30:31]
	s_waitcnt vmcnt(5)
	v_pk_add_f32 v[32:33], v[32:33], v[34:35]
	s_waitcnt vmcnt(4)
	v_pk_add_f32 v[20:21], v[36:37], v[38:39]
	v_cndmask_b32_e32 v15, v219, v15, vcc
	v_pk_add_f32 v[20:21], v[20:21], 0 op_sel_hi:[1,0]
	v_lshlrev_b32_e32 v26, 2, v15
	v_pk_add_f32 v[20:21], v[20:21], v[32:33]
	s_waitcnt vmcnt(0)
	v_pk_add_f32 v[18:19], v[52:53], v[54:55]
	v_pk_add_f32 v[20:21], v[20:21], v[28:29]
	s_nop 0
	v_pk_add_f32 v[16:17], v[20:21], v[16:17]
	s_nop 0
	v_pk_add_f32 v[16:17], v[16:17], v[18:19]
	v_pk_add_f32 v[18:19], v[48:49], v[50:51]
	s_nop 0
	v_pk_add_f32 v[16:17], v[16:17], v[18:19]
	v_pk_add_f32 v[18:19], v[44:45], v[46:47]
	s_nop 0
	v_pk_add_f32 v[16:17], v[16:17], v[18:19]
	v_pk_add_f32 v[18:19], v[40:41], v[42:43]
	s_nop 0
	v_pk_add_f32 v[16:17], v[16:17], v[18:19]
	ds_bpermute_b32 v18, v27, v16
	ds_bpermute_b32 v19, v27, v17
	s_waitcnt lgkmcnt(0)
	v_pk_add_f32 v[16:17], v[16:17], v[18:19]
	ds_bpermute_b32 v18, v26, v16
	ds_bpermute_b32 v19, v26, v17
	s_waitcnt lgkmcnt(0)
	v_pk_add_f32 v[16:17], v[16:17], v[18:19]
	s_nop 0
	v_pk_mul_f32 v[18:19], v[16:17], s[82:83] op_sel_hi:[1,0]
	v_subrev_u32_e32 v16, s0, v24
	v_fma_f32 v15, -v18, v18, v19
	v_max_f32_e32 v15, 0, v15
	v_add_f32_e32 v15, 0x3727c5ac, v15
	v_mov_b32_e32 v17, v2
	v_rsq_f32_e32 v20, v15
	v_lshl_add_u64 v[16:17], v[16:17], 1, s[70:71]
	v_ashrrev_i32_e32 v15, 31, v14
	v_lshl_add_u64 v[16:17], v[14:15], 1, v[16:17]
	global_load_dwordx2 v[28:29], v[16:17], off
	v_lshlrev_b64 v[14:15], 2, v[14:15]
	s_waitcnt vmcnt(0)
	v_lshlrev_b32_e32 v19, 16, v28
	v_and_b32_e32 v21, 0xffff0000, v28
	v_lshlrev_b32_e32 v30, 16, v29
	v_and_b32_e32 v31, 0xffff0000, v29
	v_sub_f32_e32 v29, v21, v18
	v_sub_f32_e32 v28, v19, v18
	v_sub_f32_e32 v19, v31, v18
	v_sub_f32_e32 v18, v30, v18
	v_pk_mul_f32 v[18:19], v[20:21], v[18:19] op_sel_hi:[0,1]
	v_pk_mul_f32 v[20:21], v[20:21], v[28:29] op_sel_hi:[0,1]
	v_lshl_add_u64 v[28:29], s[46:47], 0, v[14:15]
	v_lshl_add_u64 v[14:15], s[48:49], 0, v[14:15]
	global_load_dwordx4 v[28:31], v[28:29], off
	s_nop 0
	global_load_dwordx4 v[32:35], v[14:15], off
	s_waitcnt vmcnt(0)
	v_pk_fma_f32 v[14:15], v[28:29], v[20:21], v[32:33]
	v_pk_fma_f32 v[18:19], v[30:31], v[18:19], v[34:35]
	v_pk_fma_f32 v[6:7], v[14:15], s[72:73], v[6:7] op_sel_hi:[1,0,1]
	v_pk_fma_f32 v[4:5], v[18:19], s[72:73], v[4:5] op_sel_hi:[1,0,1]
	v_cvt_pk_bf16_f32 v6, v6, v7
	v_cvt_pk_bf16_f32 v7, v4, v5
	global_store_dwordx2 v[16:17], v[6:7], off
	v_lshlrev_b32_e32 v4, 16, v6
	v_and_b32_e32 v6, 0xffff0000, v6
	v_lshlrev_b32_e32 v14, 16, v7
	v_and_b32_e32 v16, 0xffff0000, v7
	v_mul_f32_e32 v5, v4, v4
	v_mul_f32_e32 v7, v6, v6
	v_mul_f32_e32 v15, v14, v14
	v_mul_f32_e32 v17, v16, v16
	v_pk_add_f32 v[4:5], v[4:5], v[6:7]
	v_pk_add_f32 v[6:7], v[14:15], v[16:17]
	s_nop 0
	v_pk_add_f32 v[4:5], v[4:5], v[6:7]
	ds_bpermute_b32 v6, v27, v4
	ds_bpermute_b32 v7, v27, v5
	s_waitcnt lgkmcnt(0)
	v_pk_add_f32 v[4:5], v[4:5], v[6:7]
	ds_bpermute_b32 v6, v26, v4
	ds_bpermute_b32 v7, v26, v5
	s_and_saveexec_b64 s[0:1], s[38:39]
	s_cbranch_execz .LBB0_2225
	s_lshl_b32 s8, s8, 1
	v_lshl_add_u64 v[12:13], s[40:41], 0, v[12:13]
	s_ashr_i32 s9, s8, 31
	v_lshl_add_u64 v[12:13], s[8:9], 2, v[12:13]
	s_waitcnt lgkmcnt(0)
	v_pk_add_f32 v[4:5], v[4:5], v[6:7]
	global_store_dwordx2 v[12:13], v[4:5], off
	s_branch .LBB0_2225

; template <int KSPLIT, class F>
; __device__ __forceinline__ void skinny_gemm(const bf16_t* A, const bf16_t* Bt, int N, int K, const F& f, LAS unsigned char* lds, int bx, int G, int wave) {
;     ...
;         const bf16_t* ap = A + (size_t)(MP + 16 * mt + fr) * K + kq * klen + 8 * fq;
;         const bf16_t* bp = Bt + (size_t)(n0 + fr) * K + kq * klen + 8 * fq;
;         f32x4 acc = (f32x4){0.f, 0.f, 0.f, 0.f};
; #pragma unroll 16
;         for (int k = 0; k < klen; k += 32) {
;             const bf16x8 af = *(const bf16x8*)(ap + k), bf = *(const bf16x8*)(bp + k);
;             acc = __builtin_amdgcn_mfma_f32_16x16x32_bf16(bf, af, acc, 0, 0, 0);
;         }
.LBB0_2306:
	global_load_dwordx4 v[180:183], v[18:19], off offset:-512
	global_load_dwordx4 v[184:187], v[16:17], off offset:-512
	global_load_dwordx4 v[188:191], v[18:19], off offset:-448
	global_load_dwordx4 v[192:195], v[16:17], off offset:-448
	global_load_dwordx4 v[196:199], v[18:19], off offset:-384
	global_load_dwordx4 v[200:203], v[16:17], off offset:-384
	global_load_dwordx4 v[204:207], v[18:19], off offset:-320
	global_load_dwordx4 v[214:217], v[16:17], off offset:-320
	global_load_dwordx4 v[234:237], v[18:19], off offset:-256
	global_load_dwordx4 v[238:241], v[16:17], off offset:-256
	global_load_dwordx4 v[242:245], v[18:19], off offset:-192
	global_load_dwordx4 v[246:249], v[16:17], off offset:-192
	s_waitcnt vmcnt(10)
	v_mfma_f32_16x16x32_bf16 v[4:7], v[184:187], v[180:183], v[4:7]
	global_load_dwordx4 v[180:183], v[18:19], off offset:-128
	global_load_dwordx4 v[184:187], v[16:17], off offset:-128
	s_waitcnt vmcnt(10)
	v_mfma_f32_16x16x32_bf16 v[4:7], v[192:195], v[188:191], v[4:7]
	global_load_dwordx4 v[188:191], v[18:19], off offset:-64
	global_load_dwordx4 v[192:195], v[16:17], off offset:-64
	s_waitcnt vmcnt(10)
	v_mfma_f32_16x16x32_bf16 v[4:7], v[200:203], v[196:199], v[4:7]
	global_load_dwordx4 v[196:199], v[18:19], off
	global_load_dwordx4 v[200:203], v[16:17], off
	s_waitcnt vmcnt(10)
	v_mfma_f32_16x16x32_bf16 v[4:7], v[214:217], v[204:207], v[4:7]
	global_load_dwordx4 v[204:207], v[18:19], off offset:64
	global_load_dwordx4 v[214:217], v[16:17], off offset:64
	s_waitcnt vmcnt(10)
	v_mfma_f32_16x16x32_bf16 v[4:7], v[238:241], v[234:237], v[4:7]
	global_load_dwordx4 v[234:237], v[18:19], off offset:128
	global_load_dwordx4 v[238:241], v[16:17], off offset:128
	s_waitcnt vmcnt(10)
	v_mfma_f32_16x16x32_bf16 v[4:7], v[246:249], v[242:245], v[4:7]
	global_load_dwordx4 v[242:245], v[18:19], off offset:192
	global_load_dwordx4 v[246:249], v[16:17], off offset:192
	s_waitcnt vmcnt(10)
	v_mfma_f32_16x16x32_bf16 v[4:7], v[184:187], v[180:183], v[4:7]
	global_load_dwordx4 v[180:183], v[18:19], off offset:256
	global_load_dwordx4 v[184:187], v[16:17], off offset:256
	s_waitcnt vmcnt(10)
	v_mfma_f32_16x16x32_bf16 v[4:7], v[192:195], v[188:191], v[4:7]
	global_load_dwordx4 v[188:191], v[18:19], off offset:320
	global_load_dwordx4 v[192:195], v[16:17], off offset:320
	s_waitcnt vmcnt(10)
	v_mfma_f32_16x16x32_bf16 v[4:7], v[200:203], v[196:199], v[4:7]
	global_load_dwordx4 v[196:199], v[18:19], off offset:384
	global_load_dwordx4 v[200:203], v[16:17], off offset:384
	s_waitcnt vmcnt(10)
	v_mfma_f32_16x16x32_bf16 v[4:7], v[214:217], v[204:207], v[4:7]
	global_load_dwordx4 v[204:207], v[18:19], off offset:448
	global_load_dwordx4 v[214:217], v[16:17], off offset:448
	s_waitcnt vmcnt(10)
	v_mfma_f32_16x16x32_bf16 v[4:7], v[238:241], v[234:237], v[4:7]
	global_load_dwordx4 v[234:237], v[18:19], off offset:512
	global_load_dwordx4 v[238:241], v[16:17], off offset:512
	s_waitcnt vmcnt(10)
	v_mfma_f32_16x16x32_bf16 v[4:7], v[246:249], v[242:245], v[4:7]
	global_load_dwordx4 v[242:245], v[18:19], off offset:576
	global_load_dwordx4 v[246:249], v[16:17], off offset:576
	s_waitcnt vmcnt(10)
	v_mfma_f32_16x16x32_bf16 v[4:7], v[184:187], v[180:183], v[4:7]
	global_load_dwordx4 v[180:183], v[18:19], off offset:640
	global_load_dwordx4 v[184:187], v[16:17], off offset:640
	s_waitcnt vmcnt(10)
	v_mfma_f32_16x16x32_bf16 v[4:7], v[192:195], v[188:191], v[4:7]
	global_load_dwordx4 v[188:191], v[18:19], off offset:704
	global_load_dwordx4 v[192:195], v[16:17], off offset:704
	s_waitcnt vmcnt(10)
	v_mfma_f32_16x16x32_bf16 v[4:7], v[200:203], v[196:199], v[4:7]
	global_load_dwordx4 v[196:199], v[18:19], off offset:768
	global_load_dwordx4 v[200:203], v[16:17], off offset:768
	s_waitcnt vmcnt(10)
	v_mfma_f32_16x16x32_bf16 v[4:7], v[214:217], v[204:207], v[4:7]
	global_load_dwordx4 v[204:207], v[18:19], off offset:832
	global_load_dwordx4 v[214:217], v[16:17], off offset:832
	s_waitcnt vmcnt(10)
	v_mfma_f32_16x16x32_bf16 v[4:7], v[238:241], v[234:237], v[4:7]
	global_load_dwordx4 v[234:237], v[18:19], off offset:896
	global_load_dwordx4 v[238:241], v[16:17], off offset:896
	s_waitcnt vmcnt(10)
	v_mfma_f32_16x16x32_bf16 v[4:7], v[246:249], v[242:245], v[4:7]
	global_load_dwordx4 v[242:245], v[18:19], off offset:960
	global_load_dwordx4 v[246:249], v[16:17], off offset:960
	s_waitcnt vmcnt(10)
	v_mfma_f32_16x16x32_bf16 v[4:7], v[184:187], v[180:183], v[4:7]
	global_load_dwordx4 v[180:183], v[18:19], off offset:1024
	global_load_dwordx4 v[184:187], v[16:17], off offset:1024
	s_waitcnt vmcnt(10)
	v_mfma_f32_16x16x32_bf16 v[4:7], v[192:195], v[188:191], v[4:7]
	global_load_dwordx4 v[188:191], v[18:19], off offset:1088
	global_load_dwordx4 v[192:195], v[16:17], off offset:1088
	s_waitcnt vmcnt(10)
; #define LAS __attribute__((address_space(3)))
; __device__ __forceinline__ void stats_sk(const float* sts, int row, int fq, float& mu, float& rs) {
;     const f32x4* p = (const f32x4*)(sts + (size_t)(row - MP) * 128 + fq * 32);
;     float s1 = 0.f, s2 = 0.f;
; #pragma unroll
;     for (int i = 0; i < 8; ++i) { const f32x4 a = p[i]; s1 += a.x + a.z; s2 += a.y + a.w; }
;     s1 += __shfl_xor(s1, 16); s2 += __shfl_xor(s2, 16); s1 += __shfl_xor(s1, 32); s2 += __shfl_xor(s2, 32);
;     mu = s1 * (1.f / DM); rs = __builtin_amdgcn_rsqf(fmaxf(s2 * (1.f / DM) - mu * mu, 0.f) + LN_EPS);
; }
; template <int KSPLIT, class F>
; __device__ __forceinline__ void skinny_gemm(const bf16_t* A, const bf16_t* Bt, int N, int K, const F& f, LAS unsigned char* lds, int bx, int G, int wave) {
;     ...
;         for (int k = 0; k < klen; k += 32) {
;             const bf16x8 af = *(const bf16x8*)(ap + k), bf = *(const bf16x8*)(bp + k);
;             acc = __builtin_amdgcn_mfma_f32_16x16x32_bf16(bf, af, acc, 0, 0, 0);
;         }
;         if (KSPLIT > 1) {
;             __syncthreads();
;             *(LAS f32x4*)(lds + wave * 1024 + lane * 16) = acc;
;             __syncthreads();
;             if (kq == 0) {
; #pragma unroll
;                 for (int q = 1; q < KSPLIT; ++q) acc = acc + *(const LAS f32x4*)(lds + (wave + q * MTW) * 1024 + lane * 16);
;                 f.sk(MP + 16 * mt + fr, n0 + 4 * fq, acc, fq);
;             }
;         } else f.sk(MP + 16 * mt + fr, n0 + 4 * fq, acc, fq);
	v_mfma_f32_16x16x32_bf16 v[4:7], v[200:203], v[196:199], v[4:7]
	global_load_dwordx4 v[196:199], v[18:19], off offset:1152
	global_load_dwordx4 v[200:203], v[16:17], off offset:1152
	s_waitcnt vmcnt(10)
	v_mfma_f32_16x16x32_bf16 v[4:7], v[214:217], v[204:207], v[4:7]
	global_load_dwordx4 v[204:207], v[18:19], off offset:1216
	global_load_dwordx4 v[214:217], v[16:17], off offset:1216
	s_waitcnt vmcnt(10)
	v_mfma_f32_16x16x32_bf16 v[4:7], v[238:241], v[234:237], v[4:7]
	global_load_dwordx4 v[234:237], v[18:19], off offset:1280
	global_load_dwordx4 v[238:241], v[16:17], off offset:1280
	s_waitcnt vmcnt(10)
	v_mfma_f32_16x16x32_bf16 v[4:7], v[246:249], v[242:245], v[4:7]
	global_load_dwordx4 v[242:245], v[18:19], off offset:1344
	global_load_dwordx4 v[246:249], v[16:17], off offset:1344
	s_waitcnt vmcnt(10)
	v_mfma_f32_16x16x32_bf16 v[4:7], v[184:187], v[180:183], v[4:7]
	global_load_dwordx4 v[180:183], v[18:19], off offset:1408
	global_load_dwordx4 v[184:187], v[16:17], off offset:1408
	s_waitcnt vmcnt(10)
	v_mfma_f32_16x16x32_bf16 v[4:7], v[192:195], v[188:191], v[4:7]
	global_load_dwordx4 v[188:191], v[18:19], off offset:1472
	global_load_dwordx4 v[192:195], v[16:17], off offset:1472
	s_waitcnt vmcnt(10)
	v_mfma_f32_16x16x32_bf16 v[4:7], v[200:203], v[196:199], v[4:7]
	s_waitcnt vmcnt(8)
	v_mfma_f32_16x16x32_bf16 v[4:7], v[214:217], v[204:207], v[4:7]
	s_waitcnt vmcnt(6)
	v_mfma_f32_16x16x32_bf16 v[4:7], v[238:241], v[234:237], v[4:7]
	s_waitcnt vmcnt(4)
	v_mfma_f32_16x16x32_bf16 v[4:7], v[246:249], v[242:245], v[4:7]
	s_waitcnt vmcnt(2)
	v_mfma_f32_16x16x32_bf16 v[4:7], v[184:187], v[180:183], v[4:7]
	s_waitcnt vmcnt(0)
	v_mfma_f32_16x16x32_bf16 v[4:7], v[192:195], v[188:191], v[4:7]
	s_nop 0
	global_load_dwordx4 v[16:19], v[0:1], off offset:48
	global_load_dwordx4 v[22:25], v[0:1], off offset:32
	global_load_dwordx4 v[26:29], v[0:1], off offset:16
	global_load_dwordx4 v[30:33], v[0:1], off
	global_load_dwordx4 v[34:37], v[0:1], off offset:112
	global_load_dwordx4 v[38:41], v[0:1], off offset:96
	global_load_dwordx4 v[42:45], v[0:1], off offset:80
	global_load_dwordx4 v[46:49], v[0:1], off offset:64
	v_lshl_add_u32 v50, s0, 4, v3
	v_ashrrev_i32_e32 v51, 31, v50
	s_add_i32 s0, s0, s26
	v_readlane_b32 s1, v254, 54
	s_cmpk_gt_i32 s0, 0xff
	s_waitcnt vmcnt(7)
	v_pk_add_f32 v[16:17], v[16:17], v[18:19]
	s_waitcnt vmcnt(6)
	v_pk_add_f32 v[22:23], v[22:23], v[24:25]
	s_waitcnt vmcnt(5)
	v_pk_add_f32 v[26:27], v[26:27], v[28:29]
	s_waitcnt vmcnt(4)
	v_pk_add_f32 v[30:31], v[30:31], v[32:33]
	v_add_u32_e32 v12, s1, v12
	v_pk_add_f32 v[30:31], v[30:31], 0 op_sel_hi:[1,0]
	s_waitcnt vmcnt(0)
	v_pk_add_f32 v[18:19], v[46:47], v[48:49]
	v_pk_add_f32 v[26:27], v[30:31], v[26:27]
	s_nop 0
	v_pk_add_f32 v[22:23], v[26:27], v[22:23]
	s_nop 0
	v_pk_add_f32 v[16:17], v[22:23], v[16:17]
	v_lshlrev_b64 v[22:23], 2, v[50:51]
	v_pk_add_f32 v[16:17], v[16:17], v[18:19]
	v_pk_add_f32 v[18:19], v[42:43], v[44:45]
	s_nop 0
	v_pk_add_f32 v[16:17], v[16:17], v[18:19]
	v_pk_add_f32 v[18:19], v[38:39], v[40:41]
	s_nop 0
	v_pk_add_f32 v[16:17], v[16:17], v[18:19]
	v_pk_add_f32 v[18:19], v[34:35], v[36:37]
	s_nop 0
	v_pk_add_f32 v[16:17], v[16:17], v[18:19]
	ds_bpermute_b32 v18, v20, v16
	ds_bpermute_b32 v19, v20, v17
	s_waitcnt lgkmcnt(0)
	v_pk_add_f32 v[16:17], v[16:17], v[18:19]
	ds_bpermute_b32 v18, v21, v16
	ds_bpermute_b32 v19, v21, v17
	s_waitcnt lgkmcnt(0)
	v_pk_add_f32 v[16:17], v[16:17], v[18:19]
	s_nop 0
	v_pk_mul_f32 v[26:27], v[16:17], s[82:83] op_sel_hi:[1,0]
	v_lshl_add_u64 v[16:17], s[42:43], 0, v[22:23]
	global_load_dwordx4 v[16:19], v[16:17], off
	v_lshl_add_u64 v[22:23], s[46:47], 0, v[22:23]
	global_load_dwordx4 v[22:25], v[22:23], off
	v_fma_f32 v13, -v26, v26, v27
	v_max_f32_e32 v13, 0, v13
	v_add_f32_e32 v13, 0x3727c5ac, v13
	v_rsq_f32_e32 v28, v13
	s_waitcnt vmcnt(1)
	v_xor_b32_e32 v19, 0x80000000, v19
	v_xor_b32_e32 v18, 0x80000000, v18
	v_pk_fma_f32 v[6:7], v[18:19], v[26:27], v[6:7] op_sel_hi:[1,0,1]
	v_pk_fma_f32 v[4:5], v[16:17], v[26:27], v[4:5] op_sel_hi:[1,0,1] neg_lo:[1,0,0] neg_hi:[1,0,0]
	s_waitcnt vmcnt(0)
	v_pk_fma_f32 v[6:7], v[6:7], v[28:29], v[24:25] op_sel_hi:[1,0,1]
	v_pk_fma_f32 v[4:5], v[4:5], v[28:29], v[22:23] op_sel_hi:[1,0,1]
	v_max_f32_e32 v6, 0, v6
	v_max_f32_e32 v4, 0, v4
	v_max_f32_e32 v5, 0, v5
	v_max_f32_e32 v7, 0, v7
	v_pk_mul_f32 v[6:7], v[6:7], v[6:7]
	v_pk_mul_f32 v[4:5], v[4:5], v[4:5]
	s_nop 0
	v_cvt_pk_bf16_f32 v4, v4, v5
	v_cvt_pk_bf16_f32 v5, v6, v7
	v_lshl_add_u64 v[6:7], v[50:51], 1, v[8:9]
	global_store_dwordx2 v[6:7], v[4:5], off
	s_cbranch_scc0 .LBB0_2305

; template <int KSPLIT, class F>
; __device__ __forceinline__ void skinny_gemm(const bf16_t* A, const bf16_t* Bt, int N, int K, const F& f, LAS unsigned char* lds, int bx, int G, int wave) {
;     ...
;         const bf16_t* ap = A + (size_t)(MP + 16 * mt + fr) * K + kq * klen + 8 * fq;
;         const bf16_t* bp = Bt + (size_t)(n0 + fr) * K + kq * klen + 8 * fq;
;         f32x4 acc = (f32x4){0.f, 0.f, 0.f, 0.f};
; #pragma unroll 16
;         for (int k = 0; k < klen; k += 32) {
;             const bf16x8 af = *(const bf16x8*)(ap + k), bf = *(const bf16x8*)(bp + k);
;             acc = __builtin_amdgcn_mfma_f32_16x16x32_bf16(bf, af, acc, 0, 0, 0);
;         }
;         if (KSPLIT > 1) {
;             __syncthreads();
.LBB0_2402:
	global_load_dwordx4 v[180:183], v[16:17], off offset:-512
	global_load_dwordx4 v[184:187], v[14:15], off offset:-512
	global_load_dwordx4 v[188:191], v[16:17], off offset:-448
	global_load_dwordx4 v[192:195], v[14:15], off offset:-448
	global_load_dwordx4 v[196:199], v[16:17], off offset:-384
	global_load_dwordx4 v[200:203], v[14:15], off offset:-384
	global_load_dwordx4 v[204:207], v[16:17], off offset:-320
	global_load_dwordx4 v[214:217], v[14:15], off offset:-320
	global_load_dwordx4 v[234:237], v[16:17], off offset:-256
	global_load_dwordx4 v[238:241], v[14:15], off offset:-256
	global_load_dwordx4 v[242:245], v[16:17], off offset:-192
	global_load_dwordx4 v[246:249], v[14:15], off offset:-192
	s_waitcnt vmcnt(10)
	v_mfma_f32_16x16x32_bf16 v[4:7], v[184:187], v[180:183], v[4:7]
	global_load_dwordx4 v[180:183], v[16:17], off offset:-128
	global_load_dwordx4 v[184:187], v[14:15], off offset:-128
	s_waitcnt vmcnt(10)
	v_mfma_f32_16x16x32_bf16 v[4:7], v[192:195], v[188:191], v[4:7]
	global_load_dwordx4 v[188:191], v[16:17], off offset:-64
	global_load_dwordx4 v[192:195], v[14:15], off offset:-64
	s_waitcnt vmcnt(10)
	v_mfma_f32_16x16x32_bf16 v[4:7], v[200:203], v[196:199], v[4:7]
	global_load_dwordx4 v[196:199], v[16:17], off
	global_load_dwordx4 v[200:203], v[14:15], off
	s_waitcnt vmcnt(10)
	v_mfma_f32_16x16x32_bf16 v[4:7], v[214:217], v[204:207], v[4:7]
	global_load_dwordx4 v[204:207], v[16:17], off offset:64
	global_load_dwordx4 v[214:217], v[14:15], off offset:64
	s_waitcnt vmcnt(10)
	v_mfma_f32_16x16x32_bf16 v[4:7], v[238:241], v[234:237], v[4:7]
	global_load_dwordx4 v[234:237], v[16:17], off offset:128
	global_load_dwordx4 v[238:241], v[14:15], off offset:128
	s_waitcnt vmcnt(10)
	v_mfma_f32_16x16x32_bf16 v[4:7], v[246:249], v[242:245], v[4:7]
	global_load_dwordx4 v[242:245], v[16:17], off offset:192
	global_load_dwordx4 v[246:249], v[14:15], off offset:192
	s_waitcnt vmcnt(10)
	v_mfma_f32_16x16x32_bf16 v[4:7], v[184:187], v[180:183], v[4:7]
	global_load_dwordx4 v[180:183], v[16:17], off offset:256
	global_load_dwordx4 v[184:187], v[14:15], off offset:256
	s_waitcnt vmcnt(10)
	v_mfma_f32_16x16x32_bf16 v[4:7], v[192:195], v[188:191], v[4:7]
	global_load_dwordx4 v[188:191], v[16:17], off offset:320
	global_load_dwordx4 v[192:195], v[14:15], off offset:320
	s_waitcnt vmcnt(10)
	v_mfma_f32_16x16x32_bf16 v[4:7], v[200:203], v[196:199], v[4:7]
	global_load_dwordx4 v[196:199], v[16:17], off offset:384
	global_load_dwordx4 v[200:203], v[14:15], off offset:384
	s_waitcnt vmcnt(10)
	v_mfma_f32_16x16x32_bf16 v[4:7], v[214:217], v[204:207], v[4:7]
	global_load_dwordx4 v[204:207], v[16:17], off offset:448
	global_load_dwordx4 v[214:217], v[14:15], off offset:448
	s_waitcnt vmcnt(10)
	v_mfma_f32_16x16x32_bf16 v[4:7], v[238:241], v[234:237], v[4:7]
	global_load_dwordx4 v[234:237], v[16:17], off offset:512
	global_load_dwordx4 v[238:241], v[14:15], off offset:512
	s_waitcnt vmcnt(10)
	v_mfma_f32_16x16x32_bf16 v[4:7], v[246:249], v[242:245], v[4:7]
	global_load_dwordx4 v[242:245], v[16:17], off offset:576
	global_load_dwordx4 v[246:249], v[14:15], off offset:576
	s_waitcnt vmcnt(10)
	v_mfma_f32_16x16x32_bf16 v[4:7], v[184:187], v[180:183], v[4:7]
	global_load_dwordx4 v[180:183], v[16:17], off offset:640
	global_load_dwordx4 v[184:187], v[14:15], off offset:640
	s_waitcnt vmcnt(10)
	v_mfma_f32_16x16x32_bf16 v[4:7], v[192:195], v[188:191], v[4:7]
	global_load_dwordx4 v[188:191], v[16:17], off offset:704
	global_load_dwordx4 v[192:195], v[14:15], off offset:704
	s_waitcnt vmcnt(10)
	v_mfma_f32_16x16x32_bf16 v[4:7], v[200:203], v[196:199], v[4:7]
	global_load_dwordx4 v[196:199], v[16:17], off offset:768
	global_load_dwordx4 v[200:203], v[14:15], off offset:768
	s_waitcnt vmcnt(10)
	v_mfma_f32_16x16x32_bf16 v[4:7], v[214:217], v[204:207], v[4:7]
	global_load_dwordx4 v[204:207], v[16:17], off offset:832
	global_load_dwordx4 v[214:217], v[14:15], off offset:832
	s_waitcnt vmcnt(10)
	v_mfma_f32_16x16x32_bf16 v[4:7], v[238:241], v[234:237], v[4:7]
	global_load_dwordx4 v[234:237], v[16:17], off offset:896
	global_load_dwordx4 v[238:241], v[14:15], off offset:896
	s_waitcnt vmcnt(10)
	v_mfma_f32_16x16x32_bf16 v[4:7], v[246:249], v[242:245], v[4:7]
	global_load_dwordx4 v[242:245], v[16:17], off offset:960
	global_load_dwordx4 v[246:249], v[14:15], off offset:960
	s_waitcnt vmcnt(10)
	v_mfma_f32_16x16x32_bf16 v[4:7], v[184:187], v[180:183], v[4:7]
	global_load_dwordx4 v[180:183], v[16:17], off offset:1024
	global_load_dwordx4 v[184:187], v[14:15], off offset:1024
	s_waitcnt vmcnt(10)
	v_mfma_f32_16x16x32_bf16 v[4:7], v[192:195], v[188:191], v[4:7]
	global_load_dwordx4 v[188:191], v[16:17], off offset:1088
	global_load_dwordx4 v[192:195], v[14:15], off offset:1088
	s_waitcnt vmcnt(10)
	v_mfma_f32_16x16x32_bf16 v[4:7], v[200:203], v[196:199], v[4:7]
	global_load_dwordx4 v[196:199], v[16:17], off offset:1152
	global_load_dwordx4 v[200:203], v[14:15], off offset:1152
	s_waitcnt vmcnt(10)
	v_mfma_f32_16x16x32_bf16 v[4:7], v[214:217], v[204:207], v[4:7]
	global_load_dwordx4 v[204:207], v[16:17], off offset:1216
	global_load_dwordx4 v[214:217], v[14:15], off offset:1216
	s_waitcnt vmcnt(10)
	v_mfma_f32_16x16x32_bf16 v[4:7], v[238:241], v[234:237], v[4:7]
	global_load_dwordx4 v[234:237], v[16:17], off offset:1280
	global_load_dwordx4 v[238:241], v[14:15], off offset:1280
	s_waitcnt vmcnt(10)
	v_mfma_f32_16x16x32_bf16 v[4:7], v[246:249], v[242:245], v[4:7]
	global_load_dwordx4 v[242:245], v[16:17], off offset:1344
	global_load_dwordx4 v[246:249], v[14:15], off offset:1344
	s_waitcnt vmcnt(10)
	v_mfma_f32_16x16x32_bf16 v[4:7], v[184:187], v[180:183], v[4:7]
	global_load_dwordx4 v[180:183], v[16:17], off offset:1408
	global_load_dwordx4 v[184:187], v[14:15], off offset:1408
	s_waitcnt vmcnt(10)
	v_mfma_f32_16x16x32_bf16 v[4:7], v[192:195], v[188:191], v[4:7]
	global_load_dwordx4 v[188:191], v[16:17], off offset:1472
	global_load_dwordx4 v[192:195], v[14:15], off offset:1472
	s_waitcnt vmcnt(10)
	v_mfma_f32_16x16x32_bf16 v[4:7], v[200:203], v[196:199], v[4:7]
	s_waitcnt vmcnt(8)
	v_mfma_f32_16x16x32_bf16 v[4:7], v[214:217], v[204:207], v[4:7]
	s_waitcnt vmcnt(6)
	v_mfma_f32_16x16x32_bf16 v[4:7], v[238:241], v[234:237], v[4:7]
	s_waitcnt vmcnt(4)
	v_mfma_f32_16x16x32_bf16 v[4:7], v[246:249], v[242:245], v[4:7]
	s_waitcnt vmcnt(2)
	v_mfma_f32_16x16x32_bf16 v[4:7], v[184:187], v[180:183], v[4:7]
	s_waitcnt vmcnt(0)
	v_mfma_f32_16x16x32_bf16 v[4:7], v[192:195], v[188:191], v[4:7]
	s_nop 0
	v_readlane_b32 s8, v253, 39
	v_readlane_b32 s9, v253, 40
	s_andn2_b64 vcc, exec, s[8:9]
	s_barrier
; #define LAS __attribute__((address_space(3)))
; __device__ __forceinline__ u32x2 pk4(f32x4 v) { u32x2 r; r.x = pk2(v.x, v.y); r.y = pk2(v.z, v.w); return r; }
;     __device__ __forceinline__ void sk(int row, int col, f32x4 v, int fq) const {
;         float mu = 0.f, rs = 1.f; if (ln) stats_sk(sts_p, row, fq, mu, rs);
;         const u32x2 raw = *(const u32x2*)(src + (size_t)row * DM + col);
;         f32x4 x = (f32x4){bflo(raw.x), bfhi(raw.x), bflo(raw.y), bfhi(raw.y)};
;         if (ln) x = (x - mu) * rs * *(const f32x4*)(g + col) + *(const f32x4*)(b + col);
;         const u32x2 pz = pk4(x * ALPHA + v);
;         *(u32x2*)(dst + (size_t)row * DM + col) = pz;
;         const float z0 = bflo(pz.x), z1 = bfhi(pz.x), z2 = bflo(pz.y), z3 = bfhi(pz.y);
;         float s1 = (z0 + z1) + (z2 + z3), s2 = (z0 * z0 + z1 * z1) + (z2 * z2 + z3 * z3);
;         s1 += __shfl_xor(s1, 16); s2 += __shfl_xor(s2, 16); s1 += __shfl_xor(s1, 32); s2 += __shfl_xor(s2, 32);
;         if (fq == 0) { float* p = sts_n + (size_t)(row - MP) * 128 + (col >> 4) * 2; p[0] = s1; p[1] = s2; }
;     }
; template <int KSPLIT, class F>
; __device__ __forceinline__ void skinny_gemm(const bf16_t* A, const bf16_t* Bt, int N, int K, const F& f, LAS unsigned char* lds, int bx, int G, int wave) {
;     ...
;             *(LAS f32x4*)(lds + wave * 1024 + lane * 16) = acc;
;             __syncthreads();
;             if (kq == 0) {
; #pragma unroll
;                 for (int q = 1; q < KSPLIT; ++q) acc = acc + *(const LAS f32x4*)(lds + (wave + q * MTW) * 1024 + lane * 16);
;                 f.sk(MP + 16 * mt + fr, n0 + 4 * fq, acc, fq);
	s_nop 2
	ds_write_b128 v24, v[4:7]
	s_waitcnt lgkmcnt(0)
	s_barrier
	s_cbranch_vccnz .LBB0_2400
	ds_read_b128 v[14:17], v24 offset:2048
	v_ashrrev_i32_e32 v13, 31, v12
	s_waitcnt lgkmcnt(0)
	v_pk_add_f32 v[16:17], v[6:7], v[16:17]
	v_pk_add_f32 v[14:15], v[4:5], v[14:15]
	ds_read_b128 v[4:7], v24 offset:4096
	s_waitcnt lgkmcnt(0)
	v_pk_add_f32 v[6:7], v[16:17], v[6:7]
	v_pk_add_f32 v[18:19], v[14:15], v[4:5]
	ds_read_b128 v[14:17], v24 offset:6144
	s_waitcnt lgkmcnt(0)
	v_pk_add_f32 v[4:5], v[6:7], v[16:17]
	v_add_u32_e32 v16, s0, v23
	s_mov_b32 s0, 0xff800000
	v_pk_add_f32 v[6:7], v[18:19], v[14:15]
	v_lshlrev_b64 v[14:15], 9, v[12:13]
	s_mov_b32 s1, -1
	v_lshl_add_u64 v[14:15], v[14:15], 0, s[0:1]
	v_lshl_add_u64 v[26:27], v[0:1], 0, v[14:15]
	global_load_dwordx4 v[18:21], v[26:27], off offset:48
	global_load_dwordx4 v[28:31], v[26:27], off offset:32
	global_load_dwordx4 v[32:35], v[26:27], off offset:16
	global_load_dwordx4 v[36:39], v[26:27], off
	global_load_dwordx4 v[40:43], v[26:27], off offset:112
	global_load_dwordx4 v[44:47], v[26:27], off offset:96
	global_load_dwordx4 v[48:51], v[26:27], off offset:80
	global_load_dwordx4 v[52:55], v[26:27], off offset:64
	v_and_b32_e32 v17, 64, v219
	v_xor_b32_e32 v13, 16, v219
	v_add_u32_e32 v17, 64, v17
	v_cmp_lt_i32_e32 vcc, v13, v17
	v_lshlrev_b32_e32 v12, 11, v12
	s_waitcnt vmcnt(7)
	v_pk_add_f32 v[18:19], v[18:19], v[20:21]
	s_waitcnt vmcnt(6)
	v_pk_add_f32 v[28:29], v[28:29], v[30:31]
	s_waitcnt vmcnt(5)
	v_pk_add_f32 v[32:33], v[32:33], v[34:35]
	s_waitcnt vmcnt(4)
	v_pk_add_f32 v[36:37], v[36:37], v[38:39]
	v_cndmask_b32_e32 v13, v219, v13, vcc
	v_pk_add_f32 v[36:37], v[36:37], 0 op_sel_hi:[1,0]
	v_lshlrev_b32_e32 v26, 2, v13
	v_pk_add_f32 v[32:33], v[36:37], v[32:33]
	s_waitcnt vmcnt(0)
	v_pk_add_f32 v[20:21], v[52:53], v[54:55]
	v_pk_add_f32 v[28:29], v[32:33], v[28:29]
	v_xor_b32_e32 v13, 32, v219
	v_pk_add_f32 v[18:19], v[28:29], v[18:19]
	v_cmp_lt_i32_e32 vcc, v13, v17
	v_pk_add_f32 v[18:19], v[18:19], v[20:21]
	v_pk_add_f32 v[20:21], v[48:49], v[50:51]
	v_cndmask_b32_e32 v13, v219, v13, vcc
	v_pk_add_f32 v[18:19], v[18:19], v[20:21]
	v_pk_add_f32 v[20:21], v[44:45], v[46:47]
	v_lshlrev_b32_e32 v25, 2, v13
	v_pk_add_f32 v[18:19], v[18:19], v[20:21]
	v_pk_add_f32 v[20:21], v[40:41], v[42:43]
	v_ashrrev_i32_e32 v17, 31, v16
	v_pk_add_f32 v[18:19], v[18:19], v[20:21]
	ds_bpermute_b32 v20, v26, v18
	ds_bpermute_b32 v21, v26, v19
	s_waitcnt lgkmcnt(0)
	v_pk_add_f32 v[18:19], v[18:19], v[20:21]
	ds_bpermute_b32 v20, v25, v18
	ds_bpermute_b32 v21, v25, v19
	s_waitcnt lgkmcnt(0)
	v_pk_add_f32 v[18:19], v[18:19], v[20:21]
	s_nop 0
	v_pk_mul_f32 v[18:19], v[18:19], s[82:83] op_sel_hi:[1,0]
	s_nop 0
	v_fma_f32 v13, -v18, v18, v19
	v_max_f32_e32 v13, 0, v13
	v_add_f32_e32 v13, 0x3727c5ac, v13
	v_rsq_f32_e32 v20, v13
	v_mov_b32_e32 v13, v2
	v_lshl_add_u64 v[12:13], s[70:71], 0, v[12:13]
	v_lshl_add_u64 v[12:13], v[16:17], 1, v[12:13]
	global_load_dwordx2 v[28:29], v[12:13], off
	v_lshlrev_b64 v[16:17], 2, v[16:17]
	s_waitcnt vmcnt(0)
	v_lshlrev_b32_e32 v19, 16, v28
	v_and_b32_e32 v21, 0xffff0000, v28
	v_lshlrev_b32_e32 v27, 16, v29
	v_and_b32_e32 v30, 0xffff0000, v29
	v_sub_f32_e32 v29, v21, v18
	v_sub_f32_e32 v28, v19, v18
	v_sub_f32_e32 v19, v30, v18
	v_sub_f32_e32 v18, v27, v18
	v_pk_mul_f32 v[18:19], v[20:21], v[18:19] op_sel_hi:[0,1]
	v_pk_mul_f32 v[20:21], v[20:21], v[28:29] op_sel_hi:[0,1]
	v_lshl_add_u64 v[28:29], s[46:47], 0, v[16:17]
	v_lshl_add_u64 v[16:17], s[48:49], 0, v[16:17]
	global_load_dwordx4 v[28:31], v[28:29], off
	s_nop 0
	global_load_dwordx4 v[32:35], v[16:17], off
	s_waitcnt vmcnt(0)
	v_pk_fma_f32 v[16:17], v[28:29], v[20:21], v[32:33]
	v_pk_fma_f32 v[18:19], v[30:31], v[18:19], v[34:35]
	v_pk_fma_f32 v[6:7], v[16:17], s[72:73], v[6:7] op_sel_hi:[1,0,1]
	v_pk_fma_f32 v[4:5], v[18:19], s[72:73], v[4:5] op_sel_hi:[1,0,1]
	v_cvt_pk_bf16_f32 v6, v6, v7
	v_cvt_pk_bf16_f32 v7, v4, v5
	global_store_dwordx2 v[12:13], v[6:7], off
	v_lshlrev_b32_e32 v4, 16, v6
	v_and_b32_e32 v6, 0xffff0000, v6
	v_lshlrev_b32_e32 v12, 16, v7
	v_and_b32_e32 v16, 0xffff0000, v7
	v_mul_f32_e32 v5, v4, v4
	v_mul_f32_e32 v7, v6, v6
	v_mul_f32_e32 v13, v12, v12
	v_mul_f32_e32 v17, v16, v16
	v_pk_add_f32 v[4:5], v[4:5], v[6:7]
	v_pk_add_f32 v[6:7], v[12:13], v[16:17]
	s_nop 0
	v_pk_add_f32 v[4:5], v[4:5], v[6:7]
	ds_bpermute_b32 v6, v26, v4
	ds_bpermute_b32 v7, v26, v5
	s_waitcnt lgkmcnt(0)
	v_pk_add_f32 v[4:5], v[4:5], v[6:7]
	ds_bpermute_b32 v6, v25, v4
	ds_bpermute_b32 v7, v25, v5
	s_and_saveexec_b64 s[0:1], s[36:37]
	s_cbranch_execz .LBB0_2399
	s_lshl_b32 s8, s4, 1
	v_lshl_add_u64 v[12:13], s[38:39], 0, v[14:15]
	s_ashr_i32 s9, s8, 31
	v_lshl_add_u64 v[12:13], s[8:9], 2, v[12:13]
	s_waitcnt lgkmcnt(0)
	v_pk_add_f32 v[4:5], v[4:5], v[6:7]
	global_store_dwordx2 v[12:13], v[4:5], off
	s_branch .LBB0_2399
